# final norm rows remapped to XCD-local 128-row blocks; XCD-local barrier also after phase 14 (12 of 14 seams local, only the phase-0 barrier is global)
# speedup vs baseline: 1.0292x; 1.0024x over previous
.LBB0_147:
	v_mov_b32_e32 v242, v232
	s_mov_b32 s76, s92
	v_readfirstlane_b32 s0, v242
	s_ashr_i32 s71, s0, 6
	s_mov_b64 s[0:1], s[42:43]
	s_add_u32 s80, s0, 0x5000000
	s_addc_u32 s81, s1, 0
	s_add_u32 s18, s0, 0x9000000
	s_addc_u32 s19, s1, 0
	s_add_u32 s96, s0, 0xd000000
	s_addc_u32 s97, s1, 0
	s_add_u32 s82, s0, 0x15000000
	s_addc_u32 s83, s1, 0
	s_cmp_gt_u32 s75, 2
	s_cselect_b64 s[2:3], -1, 0
	s_and_b32 s4, s75, 0x7ffffffd
	s_cmp_lg_u32 s4, 4
	s_cselect_b64 s[4:5], -1, 0
	s_and_b64 s[2:3], s[2:3], s[4:5]
	v_mov_b32_e32 v79, 0x260
	v_mov_b32_e32 v78, 0x700000
	v_and_b32_e32 v243, 63, v242
	s_and_b64 vcc, exec, s[2:3]
	s_mov_b64 s[2:3], -1
	s_cbranch_vccz .LBB0_424
	s_add_u32 s24, s0, 0x900000
	s_addc_u32 s25, s1, 0
	s_mov_b64 s[22:23], 0
	s_cmp_lt_i32 s75, 11
	s_mov_b64 s[8:9], 0
	s_mov_b64 s[20:21], 0
	s_mov_b64 s[26:27], 0
	s_cbranch_scc1 .LBB0_193
	s_mov_b64 s[4:5], -1
	s_cmp_gt_i32 s75, 12
	s_cbranch_scc0 .LBB0_158
	s_mov_b64 s[4:5], 0
	s_mov_b64 s[20:21], -1
	s_cmp_gt_i32 s75, 13
	s_cbranch_scc0 .LBB0_158
	s_cmp_gt_i32 s75, 14
	s_mov_b64 s[26:27], -1
	s_cbranch_scc0 .LBB0_157
	s_cmp_eq_u32 s75, 15
	s_cbranch_scc0 .LBB0_156
	v_readlane_b32 s2, v255, 4
	s_and_b32 s6, s76, 7
	s_lshl_b32 s6, s6, 5
	s_lshr_b32 s7, s76, 3
	s_add_i32 s6, s6, s7
	s_lshl_b32 s6, s6, 7
	s_lshl_b32 s7, s71, 4
	v_mov_b32_e32 v1, s2
	ds_read_b128 v[2:5], v1
	s_add_i32 s6, s7, s6
	s_add_i32 s98, s6, 16
	s_cmpk_gt_i32 s6, 0x7fff
	s_waitcnt lgkmcnt(0)
	v_readfirstlane_b32 s3, v3
	v_readfirstlane_b32 s2, v2
	v_readfirstlane_b32 s10, v5
	v_readfirstlane_b32 s11, v4
	s_cbranch_scc1 .LBB0_156
	v_lshlrev_b32_e32 v18, 4, v243
	s_nop 0
	global_load_dwordx4 v[2:5], v18, s[2:3]
	global_load_dwordx4 v[6:9], v18, s[2:3] offset:1024
	global_load_dwordx4 v[10:13], v18, s[2:3] offset:2048
	global_load_dwordx4 v[14:17], v18, s[2:3] offset:3072
	s_ashr_i32 s7, s6, 31
	s_lshl_b64 s[2:3], s[6:7], 12
	s_add_u32 s2, s11, s2
	v_mov_b32_e32 v19, v0
	s_addc_u32 s3, s10, s3
	v_lshl_add_u64 v[18:19], s[2:3], 0, v[18:19]
	s_mov_b64 s[2:3], 0x3c00
	v_lshl_add_u64 v[22:23], v[18:19], 0, s[2:3]
	s_lshl_b64 s[2:3], s[6:7], 11
	s_mov_b32 s16, 0x4000
	s_mov_b32 s20, 0x100
	s_mov_b32 s26, 0x2000
	s_lshl_b64 s[10:11], s[6:7], 6
	v_lshl_or_b32 v24, v243, 3, s2
	v_mov_b32_e32 v25, s3
	s_mov_b32 s14, 4
	s_mov_b32 s17, 0
	s_mov_b32 s21, 0
	s_mov_b32 s27, 0
	s_mov_b32 s15, 0
.LBB0_155:
	v_lshl_add_u64 v[26:27], s[0:1], 0, v[24:25]
	v_add_co_u32_e32 v28, vcc, 0x5000000, v26
	s_add_u32 s12, s0, s10
	s_nop 0
	v_addc_co_u32_e32 v29, vcc, 0, v27, vcc
	s_mov_b32 s2, 0x5001000
	s_addc_u32 s13, s1, s11
	v_add_co_u32_e32 v26, vcc, s2, v26
	s_add_u32 s2, s12, 0x700000
	s_nop 0
	v_addc_co_u32_e32 v27, vcc, 0, v27, vcc
	s_addc_u32 s3, s13, 0
	global_load_dwordx2 v[60:61], v[28:29], off
	global_load_dwordx2 v[56:57], v[28:29], off offset:512
	global_load_dwordx2 v[20:21], v[28:29], off offset:1024
	global_load_dwordx2 v[18:19], v[28:29], off offset:1536
	global_load_dwordx2 v[48:49], v[28:29], off offset:2048
	global_load_dwordx2 v[46:47], v[28:29], off offset:2560
	global_load_dwordx2 v[44:45], v[28:29], off offset:3072
	global_load_dwordx2 v[40:41], v[28:29], off offset:3584
	global_load_dwordx2 v[42:43], v[26:27], off
	global_load_dwordx2 v[38:39], v[26:27], off offset:512
	global_load_dwordx2 v[36:37], v[26:27], off offset:1024
	global_load_dwordx2 v[34:35], v[26:27], off offset:1536
	global_load_dwordx2 v[32:33], v[26:27], off offset:2048
	global_load_dwordx2 v[30:31], v[26:27], off offset:2560
	global_load_dwordx2 v[28:29], v[26:27], off offset:3072
	s_nop 0
	global_load_dwordx2 v[26:27], v[26:27], off offset:3584
	s_nop 0
	global_load_dwordx4 v[50:53], v0, s[2:3] offset:48
	global_load_dwordx4 v[62:65], v0, s[2:3] offset:32
	global_load_dwordx4 v[66:69], v0, s[2:3] offset:16
	global_load_dwordx4 v[70:73], v78, s[12:13]
	v_lshl_add_u64 v[24:25], v[24:25], 0, s[26:27]
	s_waitcnt vmcnt(2)
	v_add_f32_e32 v62, v62, v63
	s_waitcnt vmcnt(1)
	v_mov_b32_e32 v58, v67
	s_waitcnt vmcnt(0)
	v_mov_b32_e32 v54, v71
	v_mov_b32_e32 v55, v72
	v_mov_b32_e32 v71, v73
	v_mov_b32_e32 v59, v68
	v_mov_b32_e32 v67, v69
	v_pk_add_f32 v[54:55], v[54:55], v[70:71]
	v_pk_add_f32 v[58:59], v[58:59], v[66:67]
	v_pk_add_f32 v[54:55], v[54:55], v[54:55] op_sel:[0,1] op_sel_hi:[1,0]
	v_pk_add_f32 v[58:59], v[58:59], v[58:59] op_sel:[0,1] op_sel_hi:[1,0]
	v_add_f32_e32 v64, v64, v65
	v_mov_b32_e32 v55, v50
	v_mov_b32_e32 v59, v51
	v_mov_b32_e32 v63, v52
	v_mov_b32_e32 v65, v53
	v_pk_add_f32 v[50:51], v[54:55], v[58:59]
	v_pk_add_f32 v[52:53], v[62:63], v[64:65]
	s_nop 0
	v_pk_add_f32 v[50:51], v[50:51], v[52:53]
	s_nop 0
	v_add_f32_e32 v1, v50, v51
	v_fmamk_f32 v1, v1, 0x3a800000, v235
	v_cmp_gt_f32_e32 vcc, s64, v1
	v_mul_f32_e32 v50, 0x4f800000, v1
	s_nop 0
	v_cndmask_b32_e32 v1, v1, v50, vcc
	v_sqrt_f32_e32 v50, v1
	s_nop 0
	v_add_u32_e32 v51, -1, v50
	v_fma_f32 v52, -v51, v50, v1
	v_cmp_ge_f32_e64 s[2:3], 0, v52
	v_add_u32_e32 v52, 1, v50
	s_nop 0
	v_cndmask_b32_e64 v51, v50, v51, s[2:3]
	v_fma_f32 v50, -v52, v50, v1
	v_cmp_lt_f32_e64 s[2:3], 0, v50
	s_nop 1
	v_cndmask_b32_e64 v50, v51, v52, s[2:3]
	v_mul_f32_e32 v51, 0x37800000, v50
	v_cndmask_b32_e32 v50, v50, v51, vcc
	v_cmp_class_f32_e32 vcc, v1, v79
	s_nop 1
	v_cndmask_b32_e32 v1, v50, v1, vcc
	v_div_scale_f32 v50, s[2:3], v1, v1, 1.0
	v_rcp_f32_e32 v51, v50
	s_add_u32 s2, s12, 0x700040
	s_addc_u32 s3, s13, 0
	v_fma_f32 v52, -v50, v51, 1.0
	v_fmac_f32_e32 v51, v52, v51
	v_div_scale_f32 v52, vcc, 1.0, v1, 1.0
	v_mul_f32_e32 v53, v52, v51
	v_fma_f32 v54, -v50, v53, v52
	v_fmac_f32_e32 v53, v54, v51
	v_fma_f32 v50, -v50, v53, v52
	v_div_fmas_f32 v50, v50, v51, v53
	v_div_fixup_f32 v58, v50, v1, 1.0
	global_load_dwordx4 v[50:53], v0, s[2:3] offset:48
	global_load_dwordx4 v[62:65], v0, s[2:3] offset:32
	global_load_dwordx4 v[66:69], v0, s[2:3] offset:16
	global_load_dwordx4 v[70:73], v78, s[12:13] offset:64
	s_waitcnt vmcnt(2)
	v_add_f32_e32 v62, v62, v63
	v_add_f32_e32 v64, v64, v65
	s_waitcnt vmcnt(0)
	v_mov_b32_e32 v54, v71
	v_mov_b32_e32 v55, v72
	v_mov_b32_e32 v71, v73
	v_pk_add_f32 v[54:55], v[54:55], v[70:71]
	v_mov_b32_e32 v70, v67
	v_mov_b32_e32 v71, v68
	v_mov_b32_e32 v67, v69
	v_pk_add_f32 v[66:67], v[70:71], v[66:67]
	v_pk_add_f32 v[54:55], v[54:55], v[54:55] op_sel:[0,1] op_sel_hi:[1,0]
	v_pk_add_f32 v[66:67], v[66:67], v[66:67] op_sel:[0,1] op_sel_hi:[1,0]
	v_mov_b32_e32 v55, v50
	v_mov_b32_e32 v67, v51
	v_mov_b32_e32 v63, v52
	v_mov_b32_e32 v65, v53
	v_pk_add_f32 v[50:51], v[54:55], v[66:67]
	v_pk_add_f32 v[52:53], v[62:63], v[64:65]
	s_nop 0
	v_pk_add_f32 v[50:51], v[50:51], v[52:53]
	s_nop 0
	v_add_f32_e32 v1, v50, v51
	v_fmamk_f32 v1, v1, 0x3a800000, v235
	v_cmp_gt_f32_e32 vcc, s64, v1
	v_mul_f32_e32 v50, 0x4f800000, v1
	s_nop 0
	v_cndmask_b32_e32 v1, v1, v50, vcc
	v_sqrt_f32_e32 v50, v1
	s_nop 0
	v_add_u32_e32 v51, -1, v50
	v_fma_f32 v52, -v51, v50, v1
	v_cmp_ge_f32_e64 s[2:3], 0, v52
	v_add_u32_e32 v52, 1, v50
	s_nop 0
	v_cndmask_b32_e64 v51, v50, v51, s[2:3]
	v_fma_f32 v50, -v52, v50, v1
	v_cmp_lt_f32_e64 s[2:3], 0, v50
	s_nop 1
	v_cndmask_b32_e64 v50, v51, v52, s[2:3]
	v_mul_f32_e32 v51, 0x37800000, v50
	v_cndmask_b32_e32 v50, v50, v51, vcc
	v_cmp_class_f32_e32 vcc, v1, v79
	s_nop 1
	v_cndmask_b32_e32 v1, v50, v1, vcc
	v_div_scale_f32 v50, s[2:3], v1, v1, 1.0
	v_rcp_f32_e32 v51, v50
	s_add_u32 s2, s12, 0x700080
	s_addc_u32 s3, s13, 0
	v_fma_f32 v52, -v50, v51, 1.0
	v_fmac_f32_e32 v51, v52, v51
	v_div_scale_f32 v52, vcc, 1.0, v1, 1.0
	v_mul_f32_e32 v53, v52, v51
	v_fma_f32 v54, -v50, v53, v52
	v_fmac_f32_e32 v53, v54, v51
	v_fma_f32 v50, -v50, v53, v52
	v_div_fmas_f32 v50, v50, v51, v53
	v_div_fixup_f32 v54, v50, v1, 1.0
	global_load_dwordx4 v[50:53], v0, s[2:3] offset:48
	global_load_dwordx4 v[62:65], v0, s[2:3] offset:32
	global_load_dwordx4 v[66:69], v0, s[2:3] offset:16
	global_load_dwordx4 v[70:73], v78, s[12:13] offset:128
	s_waitcnt vmcnt(2)
	v_add_f32_e32 v62, v62, v63
	v_add_f32_e32 v64, v64, v65
	s_waitcnt vmcnt(0)
	v_mov_b32_e32 v74, v71
	v_mov_b32_e32 v75, v72
	v_mov_b32_e32 v71, v73
	v_mov_b32_e32 v72, v67
	v_mov_b32_e32 v73, v68
	v_mov_b32_e32 v67, v69
	v_pk_add_f32 v[70:71], v[74:75], v[70:71]
	v_pk_add_f32 v[66:67], v[72:73], v[66:67]
	v_pk_add_f32 v[70:71], v[70:71], v[70:71] op_sel:[0,1] op_sel_hi:[1,0]
	v_pk_add_f32 v[66:67], v[66:67], v[66:67] op_sel:[0,1] op_sel_hi:[1,0]
	v_mov_b32_e32 v71, v50
	v_mov_b32_e32 v67, v51
	v_mov_b32_e32 v63, v52
	v_mov_b32_e32 v65, v53
	v_pk_add_f32 v[50:51], v[70:71], v[66:67]
	v_pk_add_f32 v[52:53], v[62:63], v[64:65]
	s_nop 0
	v_pk_add_f32 v[50:51], v[50:51], v[52:53]
	s_nop 0
	v_add_f32_e32 v1, v50, v51
	v_fmamk_f32 v1, v1, 0x3a800000, v235
	v_cmp_gt_f32_e32 vcc, s64, v1
	v_mul_f32_e32 v50, 0x4f800000, v1
	s_nop 0
	v_cndmask_b32_e32 v1, v1, v50, vcc
	v_sqrt_f32_e32 v50, v1
	s_nop 0
	v_add_u32_e32 v51, -1, v50
	v_fma_f32 v52, -v51, v50, v1
	v_cmp_ge_f32_e64 s[2:3], 0, v52
	v_add_u32_e32 v52, 1, v50
	s_nop 0
	v_cndmask_b32_e64 v51, v50, v51, s[2:3]
	v_fma_f32 v50, -v52, v50, v1
	v_cmp_lt_f32_e64 s[2:3], 0, v50
	s_nop 1
	v_cndmask_b32_e64 v50, v51, v52, s[2:3]
	v_mul_f32_e32 v51, 0x37800000, v50
	v_cndmask_b32_e32 v50, v50, v51, vcc
	v_cmp_class_f32_e32 vcc, v1, v79
	s_nop 1
	v_cndmask_b32_e32 v1, v50, v1, vcc
	v_div_scale_f32 v50, s[2:3], v1, v1, 1.0
	s_add_u32 s2, s12, 0x7000c0
	s_addc_u32 s3, s13, 0
	s_nop 2
	global_load_dwordx4 v[62:65], v0, s[2:3] offset:48
	global_load_dwordx4 v[66:69], v0, s[2:3] offset:32
	global_load_dwordx4 v[70:73], v0, s[2:3] offset:16
	global_load_dwordx4 v[74:77], v78, s[12:13] offset:192
	v_rcp_f32_e32 v51, v50
	s_add_i32 s6, s6, s14
	s_add_u32 s10, s10, s20
	s_addc_u32 s11, s11, s21
	v_fma_f32 v52, -v50, v51, 1.0
	v_fmac_f32_e32 v51, v52, v51
	v_div_scale_f32 v52, vcc, 1.0, v1, 1.0
	v_mul_f32_e32 v53, v52, v51
	v_fma_f32 v55, -v50, v53, v52
	v_fmac_f32_e32 v53, v55, v51
	v_fma_f32 v50, -v50, v53, v52
	v_div_fmas_f32 v50, v50, v51, v53
	v_div_fixup_f32 v50, v50, v1, 1.0
	s_cmp_lt_i32 s6, s98
	s_waitcnt vmcnt(2)
	v_add_f32_e32 v66, v66, v67
	v_add_f32_e32 v68, v68, v69
	s_waitcnt vmcnt(0)
	v_mov_b32_e32 v52, v75
	v_mov_b32_e32 v53, v76
	v_mov_b32_e32 v75, v77
	v_pk_add_f32 v[52:53], v[52:53], v[74:75]
	v_mov_b32_e32 v74, v71
	v_mov_b32_e32 v75, v72
	v_mov_b32_e32 v71, v73
	v_pk_add_f32 v[70:71], v[74:75], v[70:71]
	v_pk_add_f32 v[52:53], v[52:53], v[52:53] op_sel:[0,1] op_sel_hi:[1,0]
	v_pk_add_f32 v[70:71], v[70:71], v[70:71] op_sel:[0,1] op_sel_hi:[1,0]
	v_mov_b32_e32 v53, v62
	v_mov_b32_e32 v71, v63
	v_mov_b32_e32 v67, v64
	v_mov_b32_e32 v69, v65
	v_pk_add_f32 v[52:53], v[52:53], v[70:71]
	v_pk_add_f32 v[62:63], v[66:67], v[68:69]
	s_nop 0
	v_pk_add_f32 v[52:53], v[52:53], v[62:63]
	v_lshlrev_b32_e32 v62, 16, v60
	v_add_f32_e32 v1, v52, v53
	v_fmamk_f32 v1, v1, 0x3a800000, v235
	v_cmp_gt_f32_e32 vcc, s64, v1
	v_mul_f32_e32 v51, 0x4f800000, v1
	v_and_b32_e32 v63, 0xffff0000, v60
	v_cndmask_b32_e32 v1, v1, v51, vcc
	v_sqrt_f32_e32 v51, v1
	v_lshlrev_b32_e32 v60, 16, v61
	v_and_b32_e32 v61, 0xffff0000, v61
	v_add_u32_e32 v52, -1, v51
	v_fma_f32 v53, -v52, v51, v1
	v_cmp_ge_f32_e64 s[2:3], 0, v53
	v_add_u32_e32 v53, 1, v51
	s_nop 0
	v_cndmask_b32_e64 v52, v51, v52, s[2:3]
	v_fma_f32 v51, -v53, v51, v1
	v_cmp_lt_f32_e64 s[2:3], 0, v51
	s_nop 1
	v_cndmask_b32_e64 v51, v52, v53, s[2:3]
	v_mul_f32_e32 v52, 0x37800000, v51
	v_cndmask_b32_e32 v51, v51, v52, vcc
	v_cmp_class_f32_e32 vcc, v1, v79
	s_nop 1
	v_cndmask_b32_e32 v1, v51, v1, vcc
	v_div_scale_f32 v51, s[2:3], v1, v1, 1.0
	v_rcp_f32_e32 v52, v51
	s_movk_i32 s2, 0xd000
	v_fma_f32 v53, -v51, v52, 1.0
	v_fmac_f32_e32 v52, v53, v52
	v_div_scale_f32 v53, vcc, 1.0, v1, 1.0
	v_mul_f32_e32 v55, v53, v52
	v_fma_f32 v59, -v51, v55, v53
	v_fmac_f32_e32 v55, v59, v52
	v_fma_f32 v51, -v51, v55, v53
	v_pk_mul_f32 v[64:65], v[58:59], v[62:63] op_sel_hi:[0,1]
	v_pk_mul_f32 v[60:61], v[58:59], v[60:61] op_sel_hi:[0,1]
	v_div_fmas_f32 v51, v51, v52, v55
	v_pk_mul_f32 v[62:63], v[4:5], v[60:61]
	v_pk_mul_f32 v[60:61], v[2:3], v[64:65]
	v_add_co_u32_e32 v64, vcc, s2, v22
	s_movk_i32 s2, 0xe000
	s_nop 0
	v_addc_co_u32_e32 v65, vcc, -1, v23, vcc
	global_store_dwordx4 v[64:65], v[60:63], off offset:-3072
	v_div_fixup_f32 v52, v51, v1, 1.0
	s_nop 0
	v_lshlrev_b32_e32 v60, 16, v56
	v_and_b32_e32 v61, 0xffff0000, v56
	v_lshlrev_b32_e32 v56, 16, v57
	v_and_b32_e32 v57, 0xffff0000, v57
	v_pk_mul_f32 v[56:57], v[58:59], v[56:57] op_sel_hi:[0,1]
	v_pk_mul_f32 v[60:61], v[58:59], v[60:61] op_sel_hi:[0,1]
	v_pk_mul_f32 v[62:63], v[8:9], v[56:57]
	v_lshlrev_b32_e32 v56, 16, v20
	v_and_b32_e32 v57, 0xffff0000, v20
	v_lshlrev_b32_e32 v20, 16, v21
	v_and_b32_e32 v21, 0xffff0000, v21
	v_pk_mul_f32 v[60:61], v[6:7], v[60:61]
	v_pk_mul_f32 v[20:21], v[58:59], v[20:21] op_sel_hi:[0,1]
	global_store_dwordx4 v[64:65], v[60:63], off offset:-2048
	v_pk_mul_f32 v[56:57], v[58:59], v[56:57] op_sel_hi:[0,1]
	s_nop 0
	v_pk_mul_f32 v[62:63], v[12:13], v[20:21]
	v_lshlrev_b32_e32 v20, 16, v18
	v_and_b32_e32 v21, 0xffff0000, v18
	v_lshlrev_b32_e32 v18, 16, v19
	v_and_b32_e32 v19, 0xffff0000, v19
	v_pk_mul_f32 v[60:61], v[10:11], v[56:57]
	v_pk_mul_f32 v[56:57], v[58:59], v[20:21] op_sel_hi:[0,1]
	v_pk_mul_f32 v[18:19], v[58:59], v[18:19] op_sel_hi:[0,1]
	v_pk_mul_f32 v[20:21], v[16:17], v[18:19]
	v_pk_mul_f32 v[18:19], v[14:15], v[56:57]
	v_add_co_u32_e32 v56, vcc, s2, v22
	s_movk_i32 s2, 0xf000
	s_nop 0
	v_addc_co_u32_e32 v57, vcc, -1, v23, vcc
	global_store_dwordx4 v[56:57], v[18:21], off offset:-4096
	global_store_dwordx4 v[64:65], v[60:63], off offset:-1024
	s_nop 0
	v_lshlrev_b32_e32 v18, 16, v48
	v_and_b32_e32 v19, 0xffff0000, v48
	v_lshlrev_b32_e32 v20, 16, v49
	v_and_b32_e32 v21, 0xffff0000, v49
	v_pk_mul_f32 v[18:19], v[54:55], v[18:19] op_sel_hi:[0,1]
	v_pk_mul_f32 v[20:21], v[54:55], v[20:21] op_sel_hi:[0,1]
	v_pk_mul_f32 v[20:21], v[4:5], v[20:21]
	v_pk_mul_f32 v[18:19], v[2:3], v[18:19]
	global_store_dwordx4 v[56:57], v[18:21], off offset:-3072
	s_nop 1
	v_lshlrev_b32_e32 v18, 16, v46
	v_and_b32_e32 v19, 0xffff0000, v46
	v_lshlrev_b32_e32 v20, 16, v47
	v_and_b32_e32 v21, 0xffff0000, v47
	v_pk_mul_f32 v[18:19], v[54:55], v[18:19] op_sel_hi:[0,1]
	v_pk_mul_f32 v[20:21], v[54:55], v[20:21] op_sel_hi:[0,1]
	v_pk_mul_f32 v[20:21], v[8:9], v[20:21]
	v_pk_mul_f32 v[18:19], v[6:7], v[18:19]
	global_store_dwordx4 v[56:57], v[18:21], off offset:-2048
	s_nop 1
	v_lshlrev_b32_e32 v18, 16, v44
	v_and_b32_e32 v19, 0xffff0000, v44
	v_lshlrev_b32_e32 v20, 16, v45
	v_and_b32_e32 v21, 0xffff0000, v45
	v_pk_mul_f32 v[18:19], v[54:55], v[18:19] op_sel_hi:[0,1]
	v_pk_mul_f32 v[20:21], v[54:55], v[20:21] op_sel_hi:[0,1]
	v_pk_mul_f32 v[20:21], v[12:13], v[20:21]
	v_pk_mul_f32 v[18:19], v[10:11], v[18:19]
	global_store_dwordx4 v[56:57], v[18:21], off offset:-1024
	s_nop 1
	v_lshlrev_b32_e32 v18, 16, v40
	v_and_b32_e32 v19, 0xffff0000, v40
	v_lshlrev_b32_e32 v20, 16, v41
	v_and_b32_e32 v21, 0xffff0000, v41
	v_pk_mul_f32 v[18:19], v[54:55], v[18:19] op_sel_hi:[0,1]
	v_pk_mul_f32 v[20:21], v[54:55], v[20:21] op_sel_hi:[0,1]
	v_pk_mul_f32 v[20:21], v[16:17], v[20:21]
	v_pk_mul_f32 v[18:19], v[14:15], v[18:19]
	global_store_dwordx4 v[56:57], v[18:21], off
	v_add_co_u32_e32 v40, vcc, s2, v22
	s_nop 0
	v_lshlrev_b32_e32 v18, 16, v42
	v_and_b32_e32 v19, 0xffff0000, v42
	v_lshlrev_b32_e32 v20, 16, v43
	v_and_b32_e32 v21, 0xffff0000, v43
	v_pk_mul_f32 v[18:19], v[50:51], v[18:19] op_sel_hi:[0,1]
	v_pk_mul_f32 v[20:21], v[50:51], v[20:21] op_sel_hi:[0,1]
	v_pk_mul_f32 v[20:21], v[4:5], v[20:21]
	v_pk_mul_f32 v[18:19], v[2:3], v[18:19]
	v_addc_co_u32_e32 v41, vcc, -1, v23, vcc
	global_store_dwordx4 v[40:41], v[18:21], off offset:-3072
	s_nop 1
	v_lshlrev_b32_e32 v18, 16, v38
	v_and_b32_e32 v19, 0xffff0000, v38
	v_lshlrev_b32_e32 v20, 16, v39
	v_and_b32_e32 v21, 0xffff0000, v39
	v_pk_mul_f32 v[18:19], v[50:51], v[18:19] op_sel_hi:[0,1]
	v_pk_mul_f32 v[20:21], v[50:51], v[20:21] op_sel_hi:[0,1]
	v_pk_mul_f32 v[20:21], v[8:9], v[20:21]
	v_pk_mul_f32 v[18:19], v[6:7], v[18:19]
	global_store_dwordx4 v[40:41], v[18:21], off offset:-2048
	s_nop 1
	v_lshlrev_b32_e32 v18, 16, v36
	v_and_b32_e32 v19, 0xffff0000, v36
	v_lshlrev_b32_e32 v20, 16, v37
	v_and_b32_e32 v21, 0xffff0000, v37
	v_pk_mul_f32 v[18:19], v[50:51], v[18:19] op_sel_hi:[0,1]
	v_pk_mul_f32 v[20:21], v[50:51], v[20:21] op_sel_hi:[0,1]
	v_pk_mul_f32 v[20:21], v[12:13], v[20:21]
	v_pk_mul_f32 v[18:19], v[10:11], v[18:19]
	global_store_dwordx4 v[40:41], v[18:21], off offset:-1024
	s_nop 1
	v_lshlrev_b32_e32 v18, 16, v34
	v_and_b32_e32 v19, 0xffff0000, v34
	v_lshlrev_b32_e32 v20, 16, v35
	v_and_b32_e32 v21, 0xffff0000, v35
	v_pk_mul_f32 v[18:19], v[50:51], v[18:19] op_sel_hi:[0,1]
	v_pk_mul_f32 v[20:21], v[50:51], v[20:21] op_sel_hi:[0,1]
	v_pk_mul_f32 v[20:21], v[16:17], v[20:21]
	v_pk_mul_f32 v[18:19], v[14:15], v[18:19]
	global_store_dwordx4 v[22:23], v[18:21], off offset:-4096
	s_nop 1
	v_lshlrev_b32_e32 v18, 16, v32
	v_and_b32_e32 v19, 0xffff0000, v32
	v_lshlrev_b32_e32 v20, 16, v33
	v_and_b32_e32 v21, 0xffff0000, v33
	v_pk_mul_f32 v[18:19], v[52:53], v[18:19] op_sel_hi:[0,1]
	v_pk_mul_f32 v[20:21], v[52:53], v[20:21] op_sel_hi:[0,1]
	v_pk_mul_f32 v[20:21], v[4:5], v[20:21]
	v_pk_mul_f32 v[18:19], v[2:3], v[18:19]
	global_store_dwordx4 v[22:23], v[18:21], off offset:-3072
	s_nop 1
	v_lshlrev_b32_e32 v18, 16, v30
	v_and_b32_e32 v19, 0xffff0000, v30
	v_lshlrev_b32_e32 v20, 16, v31
	v_and_b32_e32 v21, 0xffff0000, v31
	v_pk_mul_f32 v[18:19], v[52:53], v[18:19] op_sel_hi:[0,1]
	v_pk_mul_f32 v[20:21], v[52:53], v[20:21] op_sel_hi:[0,1]
	v_pk_mul_f32 v[20:21], v[8:9], v[20:21]
	v_pk_mul_f32 v[18:19], v[6:7], v[18:19]
	global_store_dwordx4 v[22:23], v[18:21], off offset:-2048
	s_nop 1
	v_lshlrev_b32_e32 v18, 16, v28
	v_and_b32_e32 v19, 0xffff0000, v28
	v_lshlrev_b32_e32 v20, 16, v29
	v_and_b32_e32 v21, 0xffff0000, v29
	v_pk_mul_f32 v[18:19], v[52:53], v[18:19] op_sel_hi:[0,1]
	v_pk_mul_f32 v[20:21], v[52:53], v[20:21] op_sel_hi:[0,1]
	v_pk_mul_f32 v[20:21], v[12:13], v[20:21]
	v_pk_mul_f32 v[18:19], v[10:11], v[18:19]
	global_store_dwordx4 v[22:23], v[18:21], off offset:-1024
	s_nop 1
	v_lshlrev_b32_e32 v18, 16, v26
	v_and_b32_e32 v19, 0xffff0000, v26
	v_lshlrev_b32_e32 v20, 16, v27
	v_and_b32_e32 v21, 0xffff0000, v27
	v_pk_mul_f32 v[18:19], v[52:53], v[18:19] op_sel_hi:[0,1]
	v_pk_mul_f32 v[20:21], v[52:53], v[20:21] op_sel_hi:[0,1]
	v_pk_mul_f32 v[20:21], v[16:17], v[20:21]
	v_pk_mul_f32 v[18:19], v[14:15], v[18:19]
	global_store_dwordx4 v[22:23], v[18:21], off
	v_lshl_add_u64 v[22:23], v[22:23], 0, s[16:17]
	s_cbranch_scc1 .LBB0_155

.LBB0_719:
	s_andn2_saveexec_b64 s[2:3], s[2:3]
	s_cbranch_execz .LBB0_144
	v_readlane_b32 s4, v255, 60
	s_lshr_b32 s5, 0x7fd6, s75
	s_and_b32 s5, s5, 1
	s_nop 1
	s_cmp_eq_u32 s4, 0
	s_cselect_b32 s5, s5, 0
	s_cmp_eq_u32 s5, 1
	s_cbranch_scc1 .Lbar_local
	s_mov_b64 s[2:3], exec
	buffer_wbl2 sc1
	s_waitcnt lgkmcnt(0)
	s_waitcnt vmcnt(0)
	v_mbcnt_lo_u32_b32 v1, s2, 0
	v_mbcnt_hi_u32_b32 v1, s3, v1
	v_cmp_eq_u32_e32 vcc, 0, v1
	s_and_saveexec_b64 s[4:5], vcc
	s_cbranch_execz .LBB0_722
	s_bcnt1_i32_b64 s2, s[2:3]
	v_mov_b32_e32 v3, s2
	v_readlane_b32 s2, v254, 56
	v_readlane_b32 s3, v254, 57
	s_nop 4
	global_atomic_add v3, v0, v3, s[2:3] sc0
